# lever 1 counted waits: attention QK loops keep order, lgkmcnt(0) every third k-step replaced by per-pair counted lgkmcnt waits (on top of v6)
# speedup vs baseline: 1.0074x; 1.0074x over previous
; #define LAS __attribute__((address_space(3)))
; #define FA_MFMA(a, b, c) __builtin_amdgcn_mfma_f32_32x32x16_bf16((a), (b), (c), 0, 0, 0)
; #define FA_SB() __builtin_amdgcn_sched_barrier(0)
; template <int DQK, bool HAS_LSE>
; __device__ __forceinline__ void unit(LAS unsigned char* lds, const Desc& d) {
;     ...
;         const bool active = (64 * t <= qw + 31) && (64 * t + 63 >= qw - d.W);
;         if (active) {
;             const unsigned vba = (unsigned)(unsigned long)(lds + vfo + slot * VT);
;             f32x16 p0, p1;
; #pragma unroll
;             for (int i = 0; i < 16; ++i) { p0[i] = 0.f; p1[i] = 0.f; }
;             constexpr int PF = 3;
;             bf16x8 kf0[PF], kf1[PF];
; #pragma unroll
;             for (int i = 0; i < PF; ++i) { kf0[i] = *(const LAS bf16x8*)FA_KADDR(slot, 0, i); kf1[i] = *(const LAS bf16x8*)FA_KADDR(slot, 1, i); }
;             FA_SB();
; #pragma unroll
;             for (int ks = 0; ks < NKS; ++ks) {
;                 const bf16x8 a0 = kf0[ks % PF], a1 = kf1[ks % PF];
;                 p0 = FA_MFMA(a0, qr[ks], p0); p1 = FA_MFMA(a1, qr[ks], p1);
;                 if (ks + PF < NKS) { kf0[ks % PF] = *(const LAS bf16x8*)FA_KADDR(slot, 0, ks + PF); kf1[ks % PF] = *(const LAS bf16x8*)FA_KADDR(slot, 1, ks + PF); }
;                 FA_SB();
;             }
;             s16x4 vlo[2][4], vhh[2][4];
;             vtr8_issue<0>(vba, vlo[0], vhh[0]);
;             const bool full = (64 * t + 63 <= qw) && (64 * t >= qw + 31 - d.W) && (d.slope2 == 0.f);
.LBB0_517:
	s_cmp_le_i32 s62, s65
	s_cselect_b64 s[14:15], -1, 0
	s_add_i32 s4, s62, 63
	s_cmp_ge_i32 s4, s66
	s_cselect_b64 s[24:25], -1, 0
	s_and_b64 s[14:15], s[14:15], s[24:25]
	s_andn2_b64 vcc, exec, s[14:15]
	s_cbranch_vccnz .LBB0_523
	s_lshl_b32 s5, s64, 14
	s_add_i32 s14, s5, 0
	v_add3_u32 v72, s14, v161, v160
	v_add3_u32 v76, s14, v167, v160
	ds_read_b128 v[68:71], v72
	ds_read_b128 v[72:75], v72 offset:8192
	ds_read_b128 v[132:135], v76
	ds_read_b128 v[136:139], v76 offset:8192
	v_add3_u32 v76, s14, v168, v160
	ds_read_b128 v[140:143], v76
	ds_read_b128 v[144:147], v76 offset:8192
	v_add_u32_e32 v76, s5, v175
	v_add_u32_e32 v177, 0xc000, v76
	s_waitcnt lgkmcnt(5)
	v_mfma_f32_32x32x16_bf16 v[84:99], v[68:71], v[100:103], 0
	v_add3_u32 v153, s14, v169, v160
	ds_read_b128 v[178:181], v153
	ds_read_b128 v[182:185], v153 offset:8192
	s_waitcnt lgkmcnt(5)
	v_mfma_f32_32x32x16_bf16 v[68:83], v[72:75], v[100:103], 0
	s_waitcnt lgkmcnt(4)
	v_mfma_f32_32x32x16_bf16 v[84:99], v[132:135], v[104:107], v[84:99]
	v_mfma_f32_32x32x16_bf16 v[68:83], v[136:139], v[104:107], v[68:83]
	v_add3_u32 v136, s14, v170, v160
	ds_read_b128 v[132:135], v136
	ds_read_b128 v[136:139], v136 offset:8192
	s_waitcnt lgkmcnt(4)
	v_mfma_f32_32x32x16_bf16 v[84:99], v[140:143], v[108:111], v[84:99]
	v_mfma_f32_32x32x16_bf16 v[68:83], v[144:147], v[108:111], v[68:83]
	v_add3_u32 v144, s14, v171, v160
	ds_read_b128 v[140:143], v144
	ds_read_b128 v[144:147], v144 offset:8192
	s_waitcnt lgkmcnt(4)
	v_mfma_f32_32x32x16_bf16 v[84:99], v[178:181], v[112:115], v[84:99]
	v_add3_u32 v153, s14, v172, v160
	v_mfma_f32_32x32x16_bf16 v[68:83], v[182:185], v[112:115], v[68:83]
	ds_read_b128 v[178:181], v153
	ds_read_b128 v[182:185], v153 offset:8192
	s_waitcnt lgkmcnt(4)
	v_mfma_f32_32x32x16_bf16 v[84:99], v[132:135], v[116:119], v[84:99]
	v_mfma_f32_32x32x16_bf16 v[68:83], v[136:139], v[116:119], v[68:83]
	v_add3_u32 v136, s14, v173, v160
	ds_read_b128 v[132:135], v136
	ds_read_b128 v[136:139], v136 offset:8192
	s_waitcnt lgkmcnt(4)
	v_mfma_f32_32x32x16_bf16 v[84:99], v[140:143], v[120:123], v[84:99]
	v_mfma_f32_32x32x16_bf16 v[68:83], v[144:147], v[120:123], v[68:83]
	s_waitcnt lgkmcnt(2)
	v_mfma_f32_32x32x16_bf16 v[84:99], v[178:181], v[124:127], v[84:99]
	s_waitcnt lgkmcnt(1)
	v_mfma_f32_32x32x16_bf16 v[68:83], v[182:185], v[124:127], v[68:83]
	s_waitcnt lgkmcnt(0)
	v_mfma_f32_32x32x16_bf16 v[84:99], v[132:135], v[128:131], v[84:99]
	v_mfma_f32_32x32x16_bf16 v[68:83], v[136:139], v[128:131], v[68:83]
	s_cmp_le_i32 s4, s22
	s_cselect_b64 s[4:5], -1, 0
	s_cmp_ge_i32 s62, s67
	s_cselect_b64 s[14:15], -1, 0
	ds_read_b64_tr_b16 v[144:145], v177 offset:0
	ds_read_b64_tr_b16 v[146:147], v177 offset:2048
	ds_read_b64_tr_b16 v[140:141], v177 offset:512
	ds_read_b64_tr_b16 v[142:143], v177 offset:2560
	ds_read_b64_tr_b16 v[136:137], v177 offset:1024
	ds_read_b64_tr_b16 v[138:139], v177 offset:3072
	ds_read_b64_tr_b16 v[132:133], v177 offset:1536
	ds_read_b64_tr_b16 v[134:135], v177 offset:3584
	s_and_b64 s[4:5], s[4:5], s[14:15]
	s_and_b64 s[4:5], s[4:5], s[40:41]
	s_and_b64 vcc, exec, s[4:5]
	s_cbranch_vccnz .LBB0_520
; template <int DQK, bool HAS_LSE>
; __device__ __forceinline__ void unit(LAS unsigned char* lds, const Desc& d) {
;     ...
;             if (!full) {
;                 const int dist0 = myq - 64 * t - 4 * hi;
; #pragma unroll
;                 for (int i = 0; i < 16; ++i) { const int d0 = dist0 - ((i & 3) + 8 * (i >> 2)), d1 = d0 - 32;
;                     p0[i] = ((unsigned)d0 <= (unsigned)d.W) ? __builtin_fmaf(-d.slope2, (float)d0, p0[i]) : NEG;
;                     p1[i] = ((unsigned)d1 <= (unsigned)d.W) ? __builtin_fmaf(-d.slope2, (float)d1, p1[i]) : NEG; }
;             }
	v_add_u32_e32 v153, s62, v174
	v_or_b32_e32 v178, 3, v153
	v_or_b32_e32 v179, 2, v153
	v_sub_u32_e32 v196, v155, v178
	v_or_b32_e32 v178, 9, v153
	v_sub_u32_e32 v197, v0, v179
	v_or_b32_e32 v179, 8, v153
	v_sub_u32_e32 v200, v155, v178
	v_or_b32_e32 v178, 11, v153
	v_sub_u32_e32 v201, v0, v179
	v_or_b32_e32 v179, 10, v153
	v_sub_u32_e32 v214, v155, v178
	v_or_b32_e32 v178, 17, v153
	v_sub_u32_e32 v215, v0, v179
	v_or_b32_e32 v179, 16, v153
	v_sub_u32_e32 v226, v155, v178
	v_or_b32_e32 v178, 19, v153
	v_sub_u32_e32 v227, v0, v179
	v_or_b32_e32 v179, 18, v153
	v_sub_u32_e32 v230, v155, v178
	v_or_b32_e32 v178, 25, v153
	v_sub_u32_e32 v231, v0, v179
	v_or_b32_e32 v179, 24, v153
	v_sub_u32_e32 v234, v155, v178
	v_or_b32_e32 v178, 27, v153
	v_or_b32_e32 v153, 26, v153
	v_sub_u32_e32 v238, v155, v178
	v_sub_u32_e32 v239, v0, v153
	v_sub_u32_e32 v235, v0, v179
	v_cvt_f32_i32_e32 v179, v238
	v_cvt_f32_i32_e32 v178, v239
	v_cvt_f32_i32_e32 v181, v234
	v_cvt_f32_i32_e32 v180, v235
	v_mov_b32_e32 v153, v152
	v_cvt_f32_i32_e32 v183, v230
	v_cvt_f32_i32_e32 v182, v231
	v_fma_f32 v98, v152, v178, v98
	v_fma_f32 v99, v153, v179, v99
	v_cmp_gt_u32_e32 vcc, s55, v238
	v_cvt_f32_i32_e32 v185, v226
	v_cvt_f32_i32_e32 v184, v227
	v_cndmask_b32_e32 v99, v219, v99, vcc
	v_cmp_gt_u32_e32 vcc, s55, v239
	v_fma_f32 v96, v152, v180, v96
	v_fma_f32 v97, v153, v181, v97
	v_cvt_f32_i32_e32 v187, v214
	v_cndmask_b32_e32 v98, v219, v98, vcc
	v_cmp_gt_u32_e32 vcc, s55, v234
	v_cvt_f32_i32_e32 v186, v215
	v_fma_f32 v94, v152, v182, v94
	v_fma_f32 v95, v153, v183, v95
	v_cndmask_b32_e32 v97, v219, v97, vcc
	v_cmp_gt_u32_e32 vcc, s55, v235
	v_cvt_f32_i32_e32 v189, v200
	v_cvt_f32_i32_e32 v188, v201
	v_cndmask_b32_e32 v96, v219, v96, vcc
	v_cmp_gt_u32_e32 vcc, s55, v230
	v_fma_f32 v92, v152, v184, v92
	v_fma_f32 v93, v153, v185, v93
	v_cvt_f32_i32_e32 v191, v196
	v_cndmask_b32_e32 v95, v219, v95, vcc
	v_cmp_gt_u32_e32 vcc, s55, v231
	v_cvt_f32_i32_e32 v190, v197
	v_fma_f32 v90, v152, v186, v90
	v_fma_f32 v91, v153, v187, v91
	v_cndmask_b32_e32 v94, v219, v94, vcc
	v_cmp_gt_u32_e32 vcc, s55, v226
	v_add_u32_e32 v154, -1, v176
	v_cvt_f32_i32_e32 v193, v154
	v_cndmask_b32_e32 v93, v219, v93, vcc
	v_cmp_gt_u32_e32 vcc, s55, v227
	v_cvt_f32_i32_e32 v192, v176
	v_fma_f32 v88, v152, v188, v88
	v_fma_f32 v89, v153, v189, v89
	v_cndmask_b32_e32 v92, v219, v92, vcc
	v_cmp_gt_u32_e32 vcc, s55, v214
	v_subrev_u32_e32 v240, 32, v239
	v_subrev_u32_e32 v241, 32, v238
	v_cndmask_b32_e32 v91, v219, v91, vcc
	v_cmp_gt_u32_e32 vcc, s55, v215
	v_fma_f32 v86, v152, v190, v86
	v_fma_f32 v87, v153, v191, v87
	v_cvt_f32_i32_e32 v179, v241
	v_cndmask_b32_e32 v90, v219, v90, vcc
	v_cmp_gt_u32_e32 vcc, s55, v200
	v_cvt_f32_i32_e32 v178, v240
	v_subrev_u32_e32 v236, 32, v235
	v_cndmask_b32_e32 v89, v219, v89, vcc
	v_cmp_gt_u32_e32 vcc, s55, v201
	v_subrev_u32_e32 v237, 32, v234
	v_fma_f32 v84, v156, v192, v84
	v_fma_f32 v85, v157, v193, v85
	v_cndmask_b32_e32 v88, v219, v88, vcc
	v_cmp_gt_u32_e32 vcc, s55, v196
	v_cvt_f32_i32_e32 v181, v237
	v_cvt_f32_i32_e32 v180, v236
	v_cndmask_b32_e32 v87, v219, v87, vcc
	v_cmp_gt_u32_e32 vcc, s55, v197
	v_subrev_u32_e32 v232, 32, v231
	v_subrev_u32_e32 v233, 32, v230
	v_cndmask_b32_e32 v86, v219, v86, vcc
	v_cmp_gt_u32_e32 vcc, s55, v154
	v_cvt_f32_i32_e32 v183, v233
	v_cvt_f32_i32_e32 v182, v232
	v_cndmask_b32_e32 v85, v219, v85, vcc
	v_cmp_gt_u32_e32 vcc, s55, v176
	v_fma_f32 v82, v152, v178, v82
	v_fma_f32 v83, v153, v179, v83
	v_subrev_u32_e32 v228, 32, v227
	v_cndmask_b32_e32 v84, v219, v84, vcc
	v_cmp_gt_u32_e32 vcc, s55, v241
	v_subrev_u32_e32 v229, 32, v226
	v_cvt_f32_i32_e32 v185, v229
	v_cndmask_b32_e32 v83, v219, v83, vcc
	v_cmp_gt_u32_e32 vcc, s55, v240
	v_cvt_f32_i32_e32 v184, v228
	v_fma_f32 v80, v152, v180, v80
	v_fma_f32 v81, v153, v181, v81
	v_cndmask_b32_e32 v82, v219, v82, vcc
	v_cmp_gt_u32_e32 vcc, s55, v237
	v_subrev_u32_e32 v224, 32, v215
	v_subrev_u32_e32 v225, 32, v214
	v_cndmask_b32_e32 v81, v219, v81, vcc
	v_cmp_gt_u32_e32 vcc, s55, v236
	v_cvt_f32_i32_e32 v187, v225
	v_cvt_f32_i32_e32 v186, v224
	v_fma_f32 v78, v152, v182, v78
	v_fma_f32 v79, v153, v183, v79
	v_cndmask_b32_e32 v80, v219, v80, vcc
	v_cmp_gt_u32_e32 vcc, s55, v233
	v_subrev_u32_e32 v202, 32, v201
	v_subrev_u32_e32 v203, 32, v200
	v_cndmask_b32_e32 v79, v219, v79, vcc
	v_cmp_gt_u32_e32 vcc, s55, v232
	v_cvt_f32_i32_e32 v189, v203
	v_cvt_f32_i32_e32 v188, v202
	v_fma_f32 v76, v152, v184, v76
	v_fma_f32 v77, v153, v185, v77
	v_cndmask_b32_e32 v78, v219, v78, vcc
	v_cmp_gt_u32_e32 vcc, s55, v229
	v_subrev_u32_e32 v198, 32, v197
	v_subrev_u32_e32 v199, 32, v196
	v_cndmask_b32_e32 v77, v219, v77, vcc
	v_cmp_gt_u32_e32 vcc, s55, v228
	v_cvt_f32_i32_e32 v191, v199
	v_cvt_f32_i32_e32 v190, v198
	v_fma_f32 v74, v152, v186, v74
	v_fma_f32 v75, v153, v187, v75
	v_cndmask_b32_e32 v76, v219, v76, vcc
	v_cmp_gt_u32_e32 vcc, s55, v225
	v_subrev_u32_e32 v194, 32, v176
	v_subrev_u32_e32 v195, 33, v176
	v_cndmask_b32_e32 v75, v219, v75, vcc
	v_cmp_gt_u32_e32 vcc, s55, v224
	v_cvt_f32_i32_e32 v193, v195
	v_cvt_f32_i32_e32 v192, v194
	v_fma_f32 v72, v152, v188, v72
	v_fma_f32 v73, v153, v189, v73
	v_cndmask_b32_e32 v74, v219, v74, vcc
	v_cmp_gt_u32_e32 vcc, s55, v203
	v_fma_f32 v70, v152, v190, v70
	v_fma_f32 v71, v153, v191, v71
	v_fma_f32 v68, v156, v192, v68
	v_fma_f32 v69, v157, v193, v69
	v_cndmask_b32_e32 v73, v219, v73, vcc
	v_cmp_gt_u32_e32 vcc, s55, v202
	s_nop 1
	v_cndmask_b32_e32 v72, v219, v72, vcc
	v_cmp_gt_u32_e32 vcc, s55, v199
	s_nop 1
	v_cndmask_b32_e32 v71, v219, v71, vcc
	v_cmp_gt_u32_e32 vcc, s55, v198
	s_nop 1
	v_cndmask_b32_e32 v70, v219, v70, vcc
	v_cmp_gt_u32_e32 vcc, s55, v195
	s_nop 1
	v_cndmask_b32_e32 v69, v219, v69, vcc
	v_cmp_gt_u32_e32 vcc, s55, v194
	s_nop 1
	v_cndmask_b32_e32 v68, v219, v68, vcc

; #define LAS __attribute__((address_space(3)))
; #define FA_MFMA(a, b, c) __builtin_amdgcn_mfma_f32_32x32x16_bf16((a), (b), (c), 0, 0, 0)
; #define FA_SB() __builtin_amdgcn_sched_barrier(0)
; template <int DQK, bool HAS_LSE>
; __device__ __forceinline__ void unit(LAS unsigned char* lds, const Desc& d) {
;     ...
;         const bool active = (64 * t <= qw + 31) && (64 * t + 63 >= qw - d.W);
;         if (active) {
;             const unsigned vba = (unsigned)(unsigned long)(lds + vfo + slot * VT);
;             f32x16 p0, p1;
; #pragma unroll
;             for (int i = 0; i < 16; ++i) { p0[i] = 0.f; p1[i] = 0.f; }
;             constexpr int PF = 3;
;             bf16x8 kf0[PF], kf1[PF];
; #pragma unroll
;             for (int i = 0; i < PF; ++i) { kf0[i] = *(const LAS bf16x8*)FA_KADDR(slot, 0, i); kf1[i] = *(const LAS bf16x8*)FA_KADDR(slot, 1, i); }
;             FA_SB();
; #pragma unroll
;             for (int ks = 0; ks < NKS; ++ks) {
;                 const bf16x8 a0 = kf0[ks % PF], a1 = kf1[ks % PF];
;                 p0 = FA_MFMA(a0, qr[ks], p0); p1 = FA_MFMA(a1, qr[ks], p1);
;                 if (ks + PF < NKS) { kf0[ks % PF] = *(const LAS bf16x8*)FA_KADDR(slot, 0, ks + PF); kf1[ks % PF] = *(const LAS bf16x8*)FA_KADDR(slot, 1, ks + PF); }
;                 FA_SB();
;             }
;             s16x4 vlo[2][4], vhh[2][4];
;             vtr8_issue<0>(vba, vlo[0], vhh[0]);
;             const bool full = (64 * t + 63 <= qw) && (64 * t >= qw + 31 - d.W) && (d.slope2 == 0.f);
.LBB0_1994:
	s_cmp_le_i32 s44, s66
	s_cselect_b64 s[14:15], -1, 0
	s_add_i32 s4, s44, 63
	s_cmp_ge_i32 s4, s67
	s_cselect_b64 s[24:25], -1, 0
	s_and_b64 s[14:15], s[14:15], s[24:25]
	s_andn2_b64 vcc, exec, s[14:15]
	s_cbranch_vccnz .LBB0_2000
	s_mul_i32 s5, s45, 0x6000
	s_add_i32 s5, s5, 0
	v_add3_u32 v0, s5, v178, v175
	v_add3_u32 v186, s5, v179, v175
	v_add3_u32 v189, s5, v180, v175
	ds_read_b128 v[66:69], v0
	ds_read_b128 v[70:73], v0 offset:12288
	ds_read_b128 v[146:149], v186
	ds_read_b128 v[150:153], v186 offset:12288
	ds_read_b128 v[154:157], v189
	ds_read_b128 v[158:161], v189 offset:12288
	v_lshl_add_u32 v185, s45, 14, v183
	s_waitcnt lgkmcnt(5)
	v_mfma_f32_32x32x16_bf16 v[82:97], v[66:69], v[98:101], 0
	v_add3_u32 v198, s5, v181, v175
	ds_read_b128 v[190:193], v198
	ds_read_b128 v[194:197], v198 offset:12288
	s_waitcnt lgkmcnt(5)
	v_mfma_f32_32x32x16_bf16 v[66:81], v[70:73], v[98:101], 0
	s_waitcnt lgkmcnt(4)
	v_mfma_f32_32x32x16_bf16 v[82:97], v[146:149], v[102:105], v[82:97]
	v_mfma_f32_32x32x16_bf16 v[66:81], v[150:153], v[102:105], v[66:81]
	ds_read_b128 v[146:149], v0 offset:128
	ds_read_b128 v[150:153], v0 offset:12416
	s_waitcnt lgkmcnt(4)
	v_mfma_f32_32x32x16_bf16 v[82:97], v[154:157], v[106:109], v[82:97]
	v_mfma_f32_32x32x16_bf16 v[66:81], v[158:161], v[106:109], v[66:81]
	ds_read_b128 v[154:157], v186 offset:128
	ds_read_b128 v[158:161], v186 offset:12416
	s_waitcnt lgkmcnt(4)
	v_mfma_f32_32x32x16_bf16 v[82:97], v[190:193], v[110:113], v[82:97]
	v_mfma_f32_32x32x16_bf16 v[66:81], v[194:197], v[110:113], v[66:81]
	ds_read_b128 v[190:193], v189 offset:128
	ds_read_b128 v[194:197], v189 offset:12416
	s_waitcnt lgkmcnt(4)
	v_mfma_f32_32x32x16_bf16 v[82:97], v[146:149], v[114:117], v[82:97]
	v_mfma_f32_32x32x16_bf16 v[66:81], v[150:153], v[114:117], v[66:81]
	ds_read_b128 v[146:149], v198 offset:128
	ds_read_b128 v[150:153], v198 offset:12416
	s_waitcnt lgkmcnt(4)
	v_mfma_f32_32x32x16_bf16 v[82:97], v[154:157], v[118:121], v[82:97]
	v_mfma_f32_32x32x16_bf16 v[66:81], v[158:161], v[118:121], v[66:81]
	ds_read_b128 v[154:157], v0 offset:256
	ds_read_b128 v[158:161], v0 offset:12544
	s_waitcnt lgkmcnt(4)
	v_mfma_f32_32x32x16_bf16 v[82:97], v[190:193], v[122:125], v[82:97]
	v_mfma_f32_32x32x16_bf16 v[66:81], v[194:197], v[122:125], v[66:81]
	ds_read_b128 v[190:193], v186 offset:256
	ds_read_b128 v[194:197], v186 offset:12544
	s_waitcnt lgkmcnt(4)
	v_mfma_f32_32x32x16_bf16 v[82:97], v[146:149], v[126:129], v[82:97]
	v_mfma_f32_32x32x16_bf16 v[66:81], v[150:153], v[126:129], v[66:81]
	ds_read_b128 v[146:149], v189 offset:256
	ds_read_b128 v[150:153], v189 offset:12544
	s_waitcnt lgkmcnt(4)
	v_mfma_f32_32x32x16_bf16 v[82:97], v[154:157], v[130:133], v[82:97]
	v_mfma_f32_32x32x16_bf16 v[66:81], v[158:161], v[130:133], v[66:81]
	ds_read_b128 v[154:157], v198 offset:256
	ds_read_b128 v[158:161], v198 offset:12544
	s_waitcnt lgkmcnt(4)
	v_mfma_f32_32x32x16_bf16 v[82:97], v[190:193], v[134:137], v[82:97]
	s_waitcnt lgkmcnt(3)
	v_mfma_f32_32x32x16_bf16 v[66:81], v[194:197], v[134:137], v[66:81]
	s_waitcnt lgkmcnt(2)
	v_mfma_f32_32x32x16_bf16 v[82:97], v[146:149], v[138:141], v[82:97]
	s_waitcnt lgkmcnt(1)
	v_mfma_f32_32x32x16_bf16 v[66:81], v[150:153], v[138:141], v[66:81]
	s_waitcnt lgkmcnt(0)
	v_mfma_f32_32x32x16_bf16 v[82:97], v[154:157], v[142:145], v[82:97]
	v_mfma_f32_32x32x16_bf16 v[66:81], v[158:161], v[142:145], v[66:81]
	s_cmp_le_i32 s4, s52
	s_cselect_b64 s[4:5], -1, 0
	s_cmp_ge_i32 s44, s74
	ds_read_b64_tr_b16 v[158:159], v185 offset:0
	ds_read_b64_tr_b16 v[160:161], v185 offset:2048
	ds_read_b64_tr_b16 v[154:155], v185 offset:512
	ds_read_b64_tr_b16 v[156:157], v185 offset:2560
	ds_read_b64_tr_b16 v[150:151], v185 offset:1024
	ds_read_b64_tr_b16 v[152:153], v185 offset:3072
	ds_read_b64_tr_b16 v[146:147], v185 offset:1536
	ds_read_b64_tr_b16 v[148:149], v185 offset:3584
	s_cselect_b64 s[14:15], -1, 0
	s_and_b64 s[4:5], s[4:5], s[14:15]
	s_and_b64 vcc, exec, s[4:5]
	s_cbranch_vccnz .LBB0_1997
; template <int DQK, bool HAS_LSE>
; __device__ __forceinline__ void unit(LAS unsigned char* lds, const Desc& d) {
;     ...
;             if (!full) {
;                 const int dist0 = myq - 64 * t - 4 * hi;
; #pragma unroll
;                 for (int i = 0; i < 16; ++i) { const int d0 = dist0 - ((i & 3) + 8 * (i >> 2)), d1 = d0 - 32;
;                     p0[i] = ((unsigned)d0 <= (unsigned)d.W) ? __builtin_fmaf(-d.slope2, (float)d0, p0[i]) : NEG;
;                     p1[i] = ((unsigned)d1 <= (unsigned)d.W) ? __builtin_fmaf(-d.slope2, (float)d1, p1[i]) : NEG; }
;             }
	v_add_u32_e32 v0, s44, v182
	v_or_b32_e32 v190, 3, v0
	v_or_b32_e32 v191, 2, v0
	v_sub_u32_e32 v215, v167, v190
	v_or_b32_e32 v190, 9, v0
	v_sub_u32_e32 v226, v174, v191
	v_or_b32_e32 v191, 8, v0
	v_sub_u32_e32 v229, v167, v190
	v_or_b32_e32 v190, 11, v0
	v_sub_u32_e32 v230, v174, v191
	v_or_b32_e32 v191, 10, v0
	v_sub_u32_e32 v233, v167, v190
	v_or_b32_e32 v190, 17, v0
	v_sub_u32_e32 v234, v174, v191
	v_or_b32_e32 v191, 16, v0
	v_sub_u32_e32 v237, v167, v190
	v_or_b32_e32 v190, 19, v0
	v_sub_u32_e32 v238, v174, v191
	v_or_b32_e32 v191, 18, v0
	v_sub_u32_e32 v241, v167, v190
	v_or_b32_e32 v190, 25, v0
	v_sub_u32_e32 v242, v174, v191
	v_or_b32_e32 v191, 24, v0
	v_sub_u32_e32 v245, v167, v190
	v_or_b32_e32 v190, 27, v0
	v_or_b32_e32 v0, 26, v0
	v_sub_u32_e32 v249, v167, v190
	v_sub_u32_e32 v0, v174, v0
	v_sub_u32_e32 v246, v174, v191
	v_cvt_f32_i32_e32 v191, v249
	v_cvt_f32_i32_e32 v190, v0
	v_cvt_f32_i32_e32 v193, v245
	v_cvt_f32_i32_e32 v192, v246
	v_cvt_f32_i32_e32 v195, v241
	v_cvt_f32_i32_e32 v194, v242
	v_fma_f32 v96, v190, s84, v96
	v_fma_f32 v97, v191, s84, v97
	v_cmp_gt_u32_e32 vcc, s17, v249
	v_cvt_f32_i32_e32 v197, v237
	v_cvt_f32_i32_e32 v196, v238
	v_cndmask_b32_e32 v97, v219, v97, vcc
	v_cmp_gt_u32_e32 vcc, s17, v0
	v_fma_f32 v94, v192, s84, v94
	v_fma_f32 v95, v193, s84, v95
	v_cvt_f32_i32_e32 v199, v233
	v_cndmask_b32_e32 v96, v219, v96, vcc
	v_cmp_gt_u32_e32 vcc, s17, v245
	v_cvt_f32_i32_e32 v198, v234
	v_fma_f32 v92, v194, s84, v92
	v_fma_f32 v93, v195, s84, v93
	v_cndmask_b32_e32 v95, v219, v95, vcc
	v_cmp_gt_u32_e32 vcc, s17, v246
	v_cvt_f32_i32_e32 v201, v229
	v_cvt_f32_i32_e32 v200, v230
	v_cndmask_b32_e32 v94, v219, v94, vcc
	v_cmp_gt_u32_e32 vcc, s17, v241
	v_fma_f32 v90, v196, s84, v90
	v_fma_f32 v91, v197, s84, v91
	v_cvt_f32_i32_e32 v203, v215
	v_cndmask_b32_e32 v93, v219, v93, vcc
	v_cmp_gt_u32_e32 vcc, s17, v242
	v_cvt_f32_i32_e32 v202, v226
	v_fma_f32 v88, v198, s84, v88
	v_fma_f32 v89, v199, s84, v89
	v_cndmask_b32_e32 v92, v219, v92, vcc
	v_cmp_gt_u32_e32 vcc, s17, v237
	v_add_u32_e32 v186, -1, v184
	v_cvt_f32_i32_e32 v225, v186
	v_cndmask_b32_e32 v91, v219, v91, vcc
	v_cmp_gt_u32_e32 vcc, s17, v238
	v_cvt_f32_i32_e32 v224, v184
	v_fma_f32 v86, v200, s84, v86
	v_fma_f32 v87, v201, s84, v87
	v_cndmask_b32_e32 v90, v219, v90, vcc
	v_cmp_gt_u32_e32 vcc, s17, v233
	v_subrev_u32_e32 v250, 32, v0
	v_subrev_u32_e32 v251, 32, v249
	v_cndmask_b32_e32 v89, v219, v89, vcc
	v_cmp_gt_u32_e32 vcc, s17, v234
	v_fma_f32 v84, v202, s84, v84
	v_fma_f32 v85, v203, s84, v85
	v_cvt_f32_i32_e32 v191, v251
	v_cndmask_b32_e32 v88, v219, v88, vcc
	v_cmp_gt_u32_e32 vcc, s17, v229
	v_cvt_f32_i32_e32 v190, v250
	v_subrev_u32_e32 v247, 32, v246
	v_cndmask_b32_e32 v87, v219, v87, vcc
	v_cmp_gt_u32_e32 vcc, s17, v230
	v_subrev_u32_e32 v248, 32, v245
	v_fma_f32 v82, v224, s84, v82
	v_fma_f32 v83, v225, s84, v83
	v_cndmask_b32_e32 v86, v219, v86, vcc
	v_cmp_gt_u32_e32 vcc, s17, v215
	v_cvt_f32_i32_e32 v193, v248
	v_cvt_f32_i32_e32 v192, v247
	v_cndmask_b32_e32 v85, v219, v85, vcc
	v_cmp_gt_u32_e32 vcc, s17, v226
	v_subrev_u32_e32 v243, 32, v242
	v_subrev_u32_e32 v244, 32, v241
	v_cndmask_b32_e32 v84, v219, v84, vcc
	v_cmp_gt_u32_e32 vcc, s17, v186
	v_cvt_f32_i32_e32 v195, v244
	v_cvt_f32_i32_e32 v194, v243
	v_cndmask_b32_e32 v83, v219, v83, vcc
	v_cmp_gt_u32_e32 vcc, s17, v184
	v_fma_f32 v80, v190, s84, v80
	v_fma_f32 v81, v191, s84, v81
	v_subrev_u32_e32 v239, 32, v238
	v_cndmask_b32_e32 v82, v219, v82, vcc
	v_cmp_gt_u32_e32 vcc, s17, v251
	v_subrev_u32_e32 v240, 32, v237
	v_cvt_f32_i32_e32 v197, v240
	v_cndmask_b32_e32 v81, v219, v81, vcc
	v_cmp_gt_u32_e32 vcc, s17, v250
	v_cvt_f32_i32_e32 v196, v239
	v_fma_f32 v78, v192, s84, v78
	v_fma_f32 v79, v193, s84, v79
	v_cndmask_b32_e32 v80, v219, v80, vcc
	v_cmp_gt_u32_e32 vcc, s17, v248
	v_subrev_u32_e32 v235, 32, v234
	v_subrev_u32_e32 v236, 32, v233
	v_cndmask_b32_e32 v79, v219, v79, vcc
	v_cmp_gt_u32_e32 vcc, s17, v247
	v_cvt_f32_i32_e32 v199, v236
	v_cvt_f32_i32_e32 v198, v235
	v_fma_f32 v76, v194, s84, v76
	v_fma_f32 v77, v195, s84, v77
	v_cndmask_b32_e32 v78, v219, v78, vcc
	v_cmp_gt_u32_e32 vcc, s17, v244
	v_subrev_u32_e32 v231, 32, v230
	v_subrev_u32_e32 v232, 32, v229
	v_cndmask_b32_e32 v77, v219, v77, vcc
	v_cmp_gt_u32_e32 vcc, s17, v243
	v_cvt_f32_i32_e32 v201, v232
	v_cvt_f32_i32_e32 v200, v231
	v_fma_f32 v74, v196, s84, v74
	v_fma_f32 v75, v197, s84, v75
	v_cndmask_b32_e32 v76, v219, v76, vcc
	v_cmp_gt_u32_e32 vcc, s17, v240
	v_subrev_u32_e32 v227, 32, v226
	v_subrev_u32_e32 v228, 32, v215
	v_cndmask_b32_e32 v75, v219, v75, vcc
	v_cmp_gt_u32_e32 vcc, s17, v239
	v_cvt_f32_i32_e32 v203, v228
	v_cvt_f32_i32_e32 v202, v227
	v_fma_f32 v72, v198, s84, v72
	v_fma_f32 v73, v199, s84, v73
	v_cndmask_b32_e32 v74, v219, v74, vcc
	v_cmp_gt_u32_e32 vcc, s17, v236
	v_subrev_u32_e32 v189, 32, v184
	v_subrev_u32_e32 v214, 33, v184
	v_cndmask_b32_e32 v73, v219, v73, vcc
	v_cmp_gt_u32_e32 vcc, s17, v235
	v_cvt_f32_i32_e32 v225, v214
	v_cvt_f32_i32_e32 v224, v189
	v_fma_f32 v70, v200, s84, v70
	v_fma_f32 v71, v201, s84, v71
	v_cndmask_b32_e32 v72, v219, v72, vcc
	v_cmp_gt_u32_e32 vcc, s17, v232
	v_fma_f32 v68, v202, s84, v68
	v_fma_f32 v69, v203, s84, v69
	v_fma_f32 v66, v224, s84, v66
	v_fma_f32 v67, v225, s84, v67
	v_cndmask_b32_e32 v71, v219, v71, vcc
	v_cmp_gt_u32_e32 vcc, s17, v231
	s_nop 1
	v_cndmask_b32_e32 v70, v219, v70, vcc
	v_cmp_gt_u32_e32 vcc, s17, v228
	s_nop 1
	v_cndmask_b32_e32 v69, v219, v69, vcc
	v_cmp_gt_u32_e32 vcc, s17, v227
	s_nop 1
	v_cndmask_b32_e32 v68, v219, v68, vcc
	v_cmp_gt_u32_e32 vcc, s17, v214
	s_nop 1
	v_cndmask_b32_e32 v67, v219, v67, vcc
	v_cmp_gt_u32_e32 vcc, s17, v189
	s_nop 1
	v_cndmask_b32_e32 v66, v219, v66, vcc
